# v23 + FFN-up k-loops also use the paired staging order (address temps renamed out of the staging registers)
# speedup vs baseline: 1.0132x; 1.0020x over previous
; DI f32x4 mfma16(bf16x8 a, bf16x8 b, f32x4 c) { return __builtin_amdgcn_mfma_f32_16x16x32_bf16(a, b, c, 0, 0, 0); }
; template <int MI, int NJ, bool SWAP, class AP, class BP>
; DI void gemm_main(f32x4 (&acc)[MI][NJ], const AP& ap, int a_kstep, const BP& bp, int b_kstep, int nk, bf16_t* smem) {
;     ...
;   auto sstore = [&](int buf) {
;     bf16_t* As = smem + buf * L::STAGE; bf16_t* Bs = As + L::A_ELEMS;
; #pragma unroll
;     for (int i = 0; i < CA; ++i) { const int c = tid + NTHR * i; *(u32x4*)(As + (c >> 3) * LDT + (c & 7) * 8) = oka[i] ? ra[i] : (u32x4){0u, 0u, 0u, 0u}; }
; #pragma unroll
;     for (int i = 0; i < CB; ++i) { const int c = tid + NTHR * i; *(u32x4*)(Bs + (c >> 3) * LDT + (c & 7) * 8) = rb[i]; }
;   };
;   gload(0); sstore(0); gload(nk > 1 ? 1 : 0); __syncthreads();
; #pragma unroll 1
;   for (int kt = 0; kt < nk; ++kt) {
;     const int buf = kt & 1;
;     sstore(buf ^ 1);
;     gload(kt + 2 < nk ? kt + 2 : nk - 1);
;     __builtin_amdgcn_sched_barrier(0);
;     const bf16_t* As = smem + buf * L::STAGE + (wm * 16 * MI + l15) * LDT + quad * 8;
;     const bf16_t* Bs = smem + buf * L::STAGE + L::A_ELEMS + (wn * 16 * NJ + l15) * LDT + quad * 8;
; #pragma unroll
;     for (int ks = 0; ks < 2; ++ks) {
;       if (MI * NJ >= 32 && ks == 1) asm volatile("" ::: "memory");
;       bf16x8 b[NJ];
; #pragma unroll
;       for (int j = 0; j < NJ; ++j) b[j] = *(const bf16x8*)(Bs + j * 16 * LDT + ks * 32);
; #pragma unroll
;       for (int i = 0; i < MI; ++i) {
;         const bf16x8 a = *(const bf16x8*)(As + i * 16 * LDT + ks * 32);
; #pragma unroll
;         for (int j = 0; j < NJ; ++j) acc[i][j] = SWAP ? mfma16(b[j], a, acc[i][j]) : mfma16(a, b[j], acc[i][j]);
;       }
;     }
;     __syncthreads();
;   }
.Lgm6_main:
	ds_read_b128 v[246:249], v181 offset:4608
	s_waitcnt lgkmcnt(4)
	v_mfma_f32_16x16x32_bf16 v[156:159], v[182:185], v[198:201], v[156:159]
	s_waitcnt lgkmcnt(3)
	v_mfma_f32_16x16x32_bf16 v[152:155], v[186:189], v[198:201], v[152:155]
	s_waitcnt lgkmcnt(2)
	v_mfma_f32_16x16x32_bf16 v[148:151], v[190:193], v[198:201], v[148:151]
	s_waitcnt vmcnt(7)
	v_cndmask_b32_e32 v139, 0, v139, vcc
	v_cndmask_b32_e32 v138, 0, v138, vcc
	v_cndmask_b32_e32 v137, 0, v137, vcc
	v_cndmask_b32_e32 v136, 0, v136, vcc
	s_and_b32 s31, s30, 1
	s_xor_b32 s33, s31, 1
	s_mul_i32 s33, s33, 0x12000
	v_add3_u32 v254, s33, v172, v169
	ds_write_b128 v254, v[136:139]
	s_waitcnt lgkmcnt(2)
	v_mfma_f32_16x16x32_bf16 v[144:147], v[194:197], v[198:201], v[144:147]
	ds_read_b128 v[250:253], v181 offset:6912
	v_mfma_f32_16x16x32_bf16 v[108:111], v[182:185], v[242:245], v[108:111]
	v_add3_u32 v238, s33, v173, v169
	v_add3_u32 v239, s33, v174, v169
	v_add3_u32 v255, s33, v175, v169
	s_min_u32 s33, s30, 13
	s_lshl_b32 s33, s33, 7
	s_add_u32 s34, s12, s33
	s_addc_u32 s35, s13, 0
	s_nop 0
	global_load_dwordx4 v[136:139], v176, s[34:35] offset:256
	v_mfma_f32_16x16x32_bf16 v[104:107], v[186:189], v[242:245], v[104:107]
	v_mfma_f32_16x16x32_bf16 v[100:103], v[190:193], v[242:245], v[100:103]
	v_mfma_f32_16x16x32_bf16 v[96:99], v[194:197], v[242:245], v[96:99]
	ds_read_b128 v[198:201], v181 offset:9216
	s_waitcnt lgkmcnt(3)
	v_mfma_f32_16x16x32_bf16 v[92:95], v[182:185], v[246:249], v[92:95]
	s_waitcnt vmcnt(7)
	v_cndmask_b32_e64 v127, 0, v127, s[0:1]
	v_cndmask_b32_e64 v126, 0, v126, s[0:1]
	v_cndmask_b32_e64 v125, 0, v125, s[0:1]
	v_cndmask_b32_e64 v124, 0, v124, s[0:1]
	ds_write_b128 v238, v[124:127]
	v_mfma_f32_16x16x32_bf16 v[88:91], v[186:189], v[246:249], v[88:91]
	v_mfma_f32_16x16x32_bf16 v[84:87], v[190:193], v[246:249], v[84:87]
	s_nop 0
	global_load_dwordx4 v[124:127], v177, s[34:35] offset:256
	v_mfma_f32_16x16x32_bf16 v[80:83], v[194:197], v[246:249], v[80:83]
	ds_read_b128 v[242:245], v181 offset:11520
	s_waitcnt lgkmcnt(3)
	v_mfma_f32_16x16x32_bf16 v[76:79], v[182:185], v[250:253], v[76:79]
	v_mfma_f32_16x16x32_bf16 v[72:75], v[186:189], v[250:253], v[72:75]
	v_mfma_f32_16x16x32_bf16 v[68:71], v[190:193], v[250:253], v[68:71]
	s_waitcnt vmcnt(7)
	v_cndmask_b32_e64 v115, 0, v115, s[2:3]
	v_cndmask_b32_e64 v114, 0, v114, s[2:3]
	v_cndmask_b32_e64 v113, 0, v113, s[2:3]
	v_cndmask_b32_e64 v112, 0, v112, s[2:3]
	ds_write_b128 v239, v[112:115]
	v_mfma_f32_16x16x32_bf16 v[64:67], v[194:197], v[250:253], v[64:67]
	ds_read_b128 v[246:249], v181 offset:13824
	s_waitcnt lgkmcnt(4)
	v_mfma_f32_16x16x32_bf16 v[60:63], v[182:185], v[198:201], v[60:63]
	v_mfma_f32_16x16x32_bf16 v[56:59], v[186:189], v[198:201], v[56:59]
	v_mfma_f32_16x16x32_bf16 v[52:55], v[190:193], v[198:201], v[52:55]
	v_mfma_f32_16x16x32_bf16 v[48:51], v[194:197], v[198:201], v[48:51]
	ds_read_b128 v[250:253], v181 offset:16128
	s_waitcnt lgkmcnt(3)
	v_mfma_f32_16x16x32_bf16 v[44:47], v[182:185], v[242:245], v[44:47]
	s_waitcnt vmcnt(6)
	v_cndmask_b32_e64 v112, 0, v116, s[4:5]
	v_cndmask_b32_e64 v115, 0, v119, s[4:5]
	v_cndmask_b32_e64 v114, 0, v118, s[4:5]
	v_cndmask_b32_e64 v113, 0, v117, s[4:5]
	ds_write_b128 v255, v[112:115]
	v_mfma_f32_16x16x32_bf16 v[40:43], v[186:189], v[242:245], v[40:43]
	v_mfma_f32_16x16x32_bf16 v[36:39], v[190:193], v[242:245], v[36:39]
	s_nop 0
	global_load_dwordx4 v[112:115], v178, s[34:35] offset:256
	s_nop 0
	global_load_dwordx4 v[116:119], v179, s[34:35] offset:256
	v_mfma_f32_16x16x32_bf16 v[32:35], v[194:197], v[242:245], v[32:35]
	ds_read_b128 v[198:201], v181 offset:64
	s_waitcnt lgkmcnt(3)
	v_mfma_f32_16x16x32_bf16 v[28:31], v[182:185], v[246:249], v[28:31]
	v_mfma_f32_16x16x32_bf16 v[24:27], v[186:189], v[246:249], v[24:27]
	v_mfma_f32_16x16x32_bf16 v[20:23], v[190:193], v[246:249], v[20:23]
	s_waitcnt vmcnt(7)
	ds_write_b128 v254, v[120:123] offset:36864
	v_mfma_f32_16x16x32_bf16 v[16:19], v[194:197], v[246:249], v[16:19]
	ds_read_b128 v[242:245], v181 offset:2368
	s_waitcnt lgkmcnt(4)
; DI f32x4 mfma16(bf16x8 a, bf16x8 b, f32x4 c) { return __builtin_amdgcn_mfma_f32_16x16x32_bf16(a, b, c, 0, 0, 0); }
; template <int MI, int NJ, bool SWAP, class AP, class BP>
; DI void gemm_main(f32x4 (&acc)[MI][NJ], const AP& ap, int a_kstep, const BP& bp, int b_kstep, int nk, bf16_t* smem) {
;     ...
;   auto sstore = [&](int buf) {
;     bf16_t* As = smem + buf * L::STAGE; bf16_t* Bs = As + L::A_ELEMS;
; #pragma unroll
;     for (int i = 0; i < CA; ++i) { const int c = tid + NTHR * i; *(u32x4*)(As + (c >> 3) * LDT + (c & 7) * 8) = oka[i] ? ra[i] : (u32x4){0u, 0u, 0u, 0u}; }
; #pragma unroll
;     for (int i = 0; i < CB; ++i) { const int c = tid + NTHR * i; *(u32x4*)(Bs + (c >> 3) * LDT + (c & 7) * 8) = rb[i]; }
;   };
;   gload(0); sstore(0); gload(nk > 1 ? 1 : 0); __syncthreads();
; #pragma unroll 1
;   for (int kt = 0; kt < nk; ++kt) {
;     const int buf = kt & 1;
;     sstore(buf ^ 1);
;     gload(kt + 2 < nk ? kt + 2 : nk - 1);
;     __builtin_amdgcn_sched_barrier(0);
;     const bf16_t* As = smem + buf * L::STAGE + (wm * 16 * MI + l15) * LDT + quad * 8;
;     const bf16_t* Bs = smem + buf * L::STAGE + L::A_ELEMS + (wn * 16 * NJ + l15) * LDT + quad * 8;
; #pragma unroll
;     for (int ks = 0; ks < 2; ++ks) {
;       if (MI * NJ >= 32 && ks == 1) asm volatile("" ::: "memory");
;       bf16x8 b[NJ];
; #pragma unroll
;       for (int j = 0; j < NJ; ++j) b[j] = *(const bf16x8*)(Bs + j * 16 * LDT + ks * 32);
; #pragma unroll
;       for (int i = 0; i < MI; ++i) {
;         const bf16x8 a = *(const bf16x8*)(As + i * 16 * LDT + ks * 32);
; #pragma unroll
;         for (int j = 0; j < NJ; ++j) acc[i][j] = SWAP ? mfma16(b[j], a, acc[i][j]) : mfma16(a, b[j], acc[i][j]);
;       }
;     }
;     __syncthreads();
;   }
	v_mfma_f32_16x16x32_bf16 v[12:15], v[182:185], v[250:253], v[12:15]
	ds_read_b128 v[182:185], v202 offset:36928
	s_add_u32 s34, s14, s33
	s_addc_u32 s35, s15, 0
	v_lshl_add_u64 v[120:121], v[160:161], 1, s[34:35]
	s_nop 0
	global_load_dwordx4 v[120:123], v[120:121], off offset:256
	v_mfma_f32_16x16x32_bf16 v[8:11], v[186:189], v[250:253], v[8:11]
	ds_read_b128 v[186:189], v202 offset:39232
	v_mfma_f32_16x16x32_bf16 v[4:7], v[190:193], v[250:253], v[4:7]
	ds_read_b128 v[190:193], v202 offset:41536
	v_mfma_f32_16x16x32_bf16 v[0:3], v[194:197], v[250:253], v[0:3]
	ds_read_b128 v[194:197], v202 offset:43840
	ds_read_b128 v[246:249], v181 offset:4672
	s_waitcnt lgkmcnt(4)
	v_mfma_f32_16x16x32_bf16 v[156:159], v[182:185], v[198:201], v[156:159]
	s_waitcnt vmcnt(7)
	ds_write_b128 v238, v[128:131] offset:36864
	s_waitcnt lgkmcnt(4)
	v_mfma_f32_16x16x32_bf16 v[152:155], v[186:189], v[198:201], v[152:155]
	s_waitcnt lgkmcnt(3)
	v_mfma_f32_16x16x32_bf16 v[148:151], v[190:193], v[198:201], v[148:151]
	v_lshl_add_u64 v[128:129], v[162:163], 1, s[34:35]
	s_nop 0
	global_load_dwordx4 v[128:131], v[128:129], off offset:256
	s_waitcnt lgkmcnt(2)
	v_mfma_f32_16x16x32_bf16 v[144:147], v[194:197], v[198:201], v[144:147]
	ds_read_b128 v[250:253], v181 offset:6976
	v_mfma_f32_16x16x32_bf16 v[108:111], v[182:185], v[242:245], v[108:111]
	v_mfma_f32_16x16x32_bf16 v[104:107], v[186:189], v[242:245], v[104:107]
	v_mfma_f32_16x16x32_bf16 v[100:103], v[190:193], v[242:245], v[100:103]
	s_waitcnt vmcnt(7)
	ds_write_b128 v239, v[132:135] offset:36864
	v_mfma_f32_16x16x32_bf16 v[96:99], v[194:197], v[242:245], v[96:99]
	ds_read_b128 v[198:201], v181 offset:9280
	s_waitcnt lgkmcnt(4)
	v_mfma_f32_16x16x32_bf16 v[92:95], v[182:185], v[246:249], v[92:95]
	v_lshl_add_u64 v[132:133], v[164:165], 1, s[34:35]
	s_nop 0
	global_load_dwordx4 v[132:135], v[132:133], off offset:256
	v_mfma_f32_16x16x32_bf16 v[88:91], v[186:189], v[246:249], v[88:91]
	v_mfma_f32_16x16x32_bf16 v[84:87], v[190:193], v[246:249], v[84:87]
	v_mfma_f32_16x16x32_bf16 v[80:83], v[194:197], v[246:249], v[80:83]
	ds_read_b128 v[242:245], v181 offset:11584
	s_waitcnt lgkmcnt(3)
	v_mfma_f32_16x16x32_bf16 v[76:79], v[182:185], v[250:253], v[76:79]
	s_waitcnt vmcnt(7)
	ds_write_b128 v255, v[140:143] offset:36864
	v_mfma_f32_16x16x32_bf16 v[72:75], v[186:189], v[250:253], v[72:75]
	v_mfma_f32_16x16x32_bf16 v[68:71], v[190:193], v[250:253], v[68:71]
	v_lshl_add_u64 v[140:141], v[166:167], 1, s[34:35]
	s_nop 0
	global_load_dwordx4 v[140:143], v[140:141], off offset:256
	v_mfma_f32_16x16x32_bf16 v[64:67], v[194:197], v[250:253], v[64:67]
	ds_read_b128 v[246:249], v181 offset:13888
	s_waitcnt lgkmcnt(3)
	v_mfma_f32_16x16x32_bf16 v[60:63], v[182:185], v[198:201], v[60:63]
	v_mfma_f32_16x16x32_bf16 v[56:59], v[186:189], v[198:201], v[56:59]
	v_mfma_f32_16x16x32_bf16 v[52:55], v[190:193], v[198:201], v[52:55]
	v_mfma_f32_16x16x32_bf16 v[48:51], v[194:197], v[198:201], v[48:51]
	ds_read_b128 v[250:253], v181 offset:16192
	s_waitcnt lgkmcnt(3)
	v_mfma_f32_16x16x32_bf16 v[44:47], v[182:185], v[242:245], v[44:47]
	v_mfma_f32_16x16x32_bf16 v[40:43], v[186:189], v[242:245], v[40:43]
	v_mfma_f32_16x16x32_bf16 v[36:39], v[190:193], v[242:245], v[36:39]
	v_mfma_f32_16x16x32_bf16 v[32:35], v[194:197], v[242:245], v[32:35]
	s_waitcnt lgkmcnt(0)
	s_barrier
	s_add_i32 s30, s30, 1
	s_cmp_lg_u32 s30, 16
	s_cbranch_scc0 .Lgm6_exit
	s_and_b32 s98, s30, 1
	s_mul_i32 s98, s98, 0x12000
	v_add3_u32 v181, s98, v170, v180
	v_add3_u32 v202, s98, v171, v180
	ds_read_b128 v[198:201], v181
	ds_read_b128 v[242:245], v181 offset:2304
	v_mfma_f32_16x16x32_bf16 v[28:31], v[182:185], v[246:249], v[28:31]
	v_mfma_f32_16x16x32_bf16 v[12:15], v[182:185], v[250:253], v[12:15]
	ds_read_b128 v[182:185], v202 offset:36864
	v_mfma_f32_16x16x32_bf16 v[24:27], v[186:189], v[246:249], v[24:27]
	v_mfma_f32_16x16x32_bf16 v[8:11], v[186:189], v[250:253], v[8:11]
	ds_read_b128 v[186:189], v202 offset:39168
	v_mfma_f32_16x16x32_bf16 v[20:23], v[190:193], v[246:249], v[20:23]
	v_mfma_f32_16x16x32_bf16 v[4:7], v[190:193], v[250:253], v[4:7]
	ds_read_b128 v[190:193], v202 offset:41472
	v_mfma_f32_16x16x32_bf16 v[16:19], v[194:197], v[246:249], v[16:19]
	v_mfma_f32_16x16x32_bf16 v[0:3], v[194:197], v[250:253], v[0:3]
	ds_read_b128 v[194:197], v202 offset:43776
	s_branch .Lgm6_main

; DI f32x4 mfma16(bf16x8 a, bf16x8 b, f32x4 c) { return __builtin_amdgcn_mfma_f32_16x16x32_bf16(a, b, c, 0, 0, 0); }
; template <int MI, int NJ, bool SWAP, class AP, class BP>
; DI void gemm_main(f32x4 (&acc)[MI][NJ], const AP& ap, int a_kstep, const BP& bp, int b_kstep, int nk, bf16_t* smem) {
;     ...
;   auto sstore = [&](int buf) {
;     bf16_t* As = smem + buf * L::STAGE; bf16_t* Bs = As + L::A_ELEMS;
; #pragma unroll
;     for (int i = 0; i < CA; ++i) { const int c = tid + NTHR * i; *(u32x4*)(As + (c >> 3) * LDT + (c & 7) * 8) = oka[i] ? ra[i] : (u32x4){0u, 0u, 0u, 0u}; }
; #pragma unroll
;     for (int i = 0; i < CB; ++i) { const int c = tid + NTHR * i; *(u32x4*)(Bs + (c >> 3) * LDT + (c & 7) * 8) = rb[i]; }
;   };
;   gload(0); sstore(0); gload(nk > 1 ? 1 : 0); __syncthreads();
; #pragma unroll 1
;   for (int kt = 0; kt < nk; ++kt) {
;     const int buf = kt & 1;
;     sstore(buf ^ 1);
;     gload(kt + 2 < nk ? kt + 2 : nk - 1);
;     __builtin_amdgcn_sched_barrier(0);
;     const bf16_t* As = smem + buf * L::STAGE + (wm * 16 * MI + l15) * LDT + quad * 8;
;     const bf16_t* Bs = smem + buf * L::STAGE + L::A_ELEMS + (wn * 16 * NJ + l15) * LDT + quad * 8;
; #pragma unroll
;     for (int ks = 0; ks < 2; ++ks) {
;       if (MI * NJ >= 32 && ks == 1) asm volatile("" ::: "memory");
;       bf16x8 b[NJ];
; #pragma unroll
;       for (int j = 0; j < NJ; ++j) b[j] = *(const bf16x8*)(Bs + j * 16 * LDT + ks * 32);
; #pragma unroll
;       for (int i = 0; i < MI; ++i) {
;         const bf16x8 a = *(const bf16x8*)(As + i * 16 * LDT + ks * 32);
; #pragma unroll
;         for (int j = 0; j < NJ; ++j) acc[i][j] = SWAP ? mfma16(b[j], a, acc[i][j]) : mfma16(a, b[j], acc[i][j]);
;       }
;     }
;     __syncthreads();
;   }
.Lgm14_main:
	ds_read_b128 v[242:245], v181 offset:4608
	s_waitcnt lgkmcnt(4)
	v_mfma_f32_16x16x32_bf16 v[156:159], v[182:185], v[198:201], v[156:159]
	s_waitcnt lgkmcnt(3)
	v_mfma_f32_16x16x32_bf16 v[152:155], v[186:189], v[198:201], v[152:155]
	s_waitcnt lgkmcnt(2)
	v_mfma_f32_16x16x32_bf16 v[148:151], v[190:193], v[198:201], v[148:151]
	s_waitcnt vmcnt(7)
	v_cndmask_b32_e32 v143, 0, v143, vcc
	v_cndmask_b32_e32 v142, 0, v142, vcc
	v_cndmask_b32_e32 v141, 0, v141, vcc
	v_cndmask_b32_e32 v140, 0, v140, vcc
	s_and_b32 s46, s43, 1
	s_min_u32 s44, s43, 13
	s_xor_b32 s45, s46, 1
	s_mul_i32 s45, s45, 0x12000
	v_add3_u32 v250, s45, v172, v169
	ds_write_b128 v250, v[140:143]
	s_waitcnt lgkmcnt(2)
	v_mfma_f32_16x16x32_bf16 v[144:147], v[194:197], v[198:201], v[144:147]
	ds_read_b128 v[246:249], v181 offset:6912
	v_mfma_f32_16x16x32_bf16 v[108:111], v[182:185], v[202:205], v[108:111]
	s_lshl_b32 s47, s44, 7
	s_add_u32 s44, s18, s47
	v_add3_u32 v251, s45, v173, v169
	v_add3_u32 v252, s45, v174, v169
	v_add3_u32 v253, s45, v175, v169
	s_addc_u32 s45, s19, 0
	s_nop 0
	global_load_dwordx4 v[140:143], v176, s[44:45] offset:256
	v_mfma_f32_16x16x32_bf16 v[104:107], v[186:189], v[202:205], v[104:107]
	v_mfma_f32_16x16x32_bf16 v[100:103], v[190:193], v[202:205], v[100:103]
	v_mfma_f32_16x16x32_bf16 v[96:99], v[194:197], v[202:205], v[96:99]
	ds_read_b128 v[198:201], v181 offset:9216
	s_waitcnt lgkmcnt(3)
	v_mfma_f32_16x16x32_bf16 v[92:95], v[182:185], v[242:245], v[92:95]
	s_waitcnt vmcnt(7)
	v_cndmask_b32_e64 v131, 0, v131, s[0:1]
	v_cndmask_b32_e64 v130, 0, v130, s[0:1]
	v_cndmask_b32_e64 v129, 0, v129, s[0:1]
	v_cndmask_b32_e64 v128, 0, v128, s[0:1]
	ds_write_b128 v251, v[128:131]
	v_mfma_f32_16x16x32_bf16 v[88:91], v[186:189], v[242:245], v[88:91]
	v_mfma_f32_16x16x32_bf16 v[84:87], v[190:193], v[242:245], v[84:87]
	s_nop 0
	global_load_dwordx4 v[128:131], v177, s[44:45] offset:256
	v_mfma_f32_16x16x32_bf16 v[80:83], v[194:197], v[242:245], v[80:83]
	ds_read_b128 v[202:205], v181 offset:11520
	s_waitcnt lgkmcnt(3)
	v_mfma_f32_16x16x32_bf16 v[76:79], v[182:185], v[246:249], v[76:79]
	v_mfma_f32_16x16x32_bf16 v[72:75], v[186:189], v[246:249], v[72:75]
	v_mfma_f32_16x16x32_bf16 v[68:71], v[190:193], v[246:249], v[68:71]
	s_waitcnt vmcnt(7)
	v_cndmask_b32_e64 v115, 0, v115, s[2:3]
	v_cndmask_b32_e64 v114, 0, v114, s[2:3]
	v_cndmask_b32_e64 v113, 0, v113, s[2:3]
	v_cndmask_b32_e64 v112, 0, v112, s[2:3]
	ds_write_b128 v252, v[112:115]
	v_mfma_f32_16x16x32_bf16 v[64:67], v[194:197], v[246:249], v[64:67]
	ds_read_b128 v[242:245], v181 offset:13824
	s_waitcnt lgkmcnt(4)
	v_mfma_f32_16x16x32_bf16 v[60:63], v[182:185], v[198:201], v[60:63]
	s_nop 0
	global_load_dwordx4 v[112:115], v178, s[44:45] offset:256
	v_mfma_f32_16x16x32_bf16 v[56:59], v[186:189], v[198:201], v[56:59]
	v_mfma_f32_16x16x32_bf16 v[52:55], v[190:193], v[198:201], v[52:55]
	v_mfma_f32_16x16x32_bf16 v[48:51], v[194:197], v[198:201], v[48:51]
	ds_read_b128 v[246:249], v181 offset:16128
	s_waitcnt lgkmcnt(3)
	v_mfma_f32_16x16x32_bf16 v[44:47], v[182:185], v[202:205], v[44:47]
	s_waitcnt vmcnt(7)
	v_cndmask_b32_e64 v135, 0, v135, s[4:5]
	v_cndmask_b32_e64 v134, 0, v134, s[4:5]
	v_cndmask_b32_e64 v133, 0, v133, s[4:5]
	v_cndmask_b32_e64 v132, 0, v132, s[4:5]
	ds_write_b128 v253, v[132:135]
	v_mfma_f32_16x16x32_bf16 v[40:43], v[186:189], v[202:205], v[40:43]
	v_mfma_f32_16x16x32_bf16 v[36:39], v[190:193], v[202:205], v[36:39]
	s_nop 0
	global_load_dwordx4 v[132:135], v179, s[44:45] offset:256
	v_mfma_f32_16x16x32_bf16 v[32:35], v[194:197], v[202:205], v[32:35]
	ds_read_b128 v[198:201], v181 offset:64
	s_waitcnt lgkmcnt(3)
	v_mfma_f32_16x16x32_bf16 v[28:31], v[182:185], v[242:245], v[28:31]
	v_mfma_f32_16x16x32_bf16 v[24:27], v[186:189], v[242:245], v[24:27]
	v_mfma_f32_16x16x32_bf16 v[20:23], v[190:193], v[242:245], v[20:23]
	s_waitcnt vmcnt(7)
	ds_write_b128 v250, v[116:119] offset:36864
	v_mfma_f32_16x16x32_bf16 v[12:15], v[194:197], v[242:245], v[12:15]
	ds_read_b128 v[202:205], v181 offset:2368
	s_waitcnt lgkmcnt(4)
; DI f32x4 mfma16(bf16x8 a, bf16x8 b, f32x4 c) { return __builtin_amdgcn_mfma_f32_16x16x32_bf16(a, b, c, 0, 0, 0); }
; template <int MI, int NJ, bool SWAP, class AP, class BP>
; DI void gemm_main(f32x4 (&acc)[MI][NJ], const AP& ap, int a_kstep, const BP& bp, int b_kstep, int nk, bf16_t* smem) {
;     ...
;   auto sstore = [&](int buf) {
;     bf16_t* As = smem + buf * L::STAGE; bf16_t* Bs = As + L::A_ELEMS;
; #pragma unroll
;     for (int i = 0; i < CA; ++i) { const int c = tid + NTHR * i; *(u32x4*)(As + (c >> 3) * LDT + (c & 7) * 8) = oka[i] ? ra[i] : (u32x4){0u, 0u, 0u, 0u}; }
; #pragma unroll
;     for (int i = 0; i < CB; ++i) { const int c = tid + NTHR * i; *(u32x4*)(Bs + (c >> 3) * LDT + (c & 7) * 8) = rb[i]; }
;   };
;   gload(0); sstore(0); gload(nk > 1 ? 1 : 0); __syncthreads();
; #pragma unroll 1
;   for (int kt = 0; kt < nk; ++kt) {
;     const int buf = kt & 1;
;     sstore(buf ^ 1);
;     gload(kt + 2 < nk ? kt + 2 : nk - 1);
;     __builtin_amdgcn_sched_barrier(0);
;     const bf16_t* As = smem + buf * L::STAGE + (wm * 16 * MI + l15) * LDT + quad * 8;
;     const bf16_t* Bs = smem + buf * L::STAGE + L::A_ELEMS + (wn * 16 * NJ + l15) * LDT + quad * 8;
; #pragma unroll
;     for (int ks = 0; ks < 2; ++ks) {
;       if (MI * NJ >= 32 && ks == 1) asm volatile("" ::: "memory");
;       bf16x8 b[NJ];
; #pragma unroll
;       for (int j = 0; j < NJ; ++j) b[j] = *(const bf16x8*)(Bs + j * 16 * LDT + ks * 32);
; #pragma unroll
;       for (int i = 0; i < MI; ++i) {
;         const bf16x8 a = *(const bf16x8*)(As + i * 16 * LDT + ks * 32);
; #pragma unroll
;         for (int j = 0; j < NJ; ++j) acc[i][j] = SWAP ? mfma16(b[j], a, acc[i][j]) : mfma16(a, b[j], acc[i][j]);
;       }
;     }
;     __syncthreads();
;   }
	v_mfma_f32_16x16x32_bf16 v[8:11], v[182:185], v[246:249], v[8:11]
	ds_read_b128 v[182:185], v206 offset:36928
	s_add_u32 s44, s20, s47
	s_addc_u32 s45, s21, 0
	v_lshl_add_u64 v[116:117], v[160:161], 1, s[44:45]
	s_nop 0
	global_load_dwordx4 v[116:119], v[116:117], off offset:256
	v_mfma_f32_16x16x32_bf16 v[4:7], v[186:189], v[246:249], v[4:7]
	ds_read_b128 v[186:189], v206 offset:39232
	v_mfma_f32_16x16x32_bf16 v[0:3], v[190:193], v[246:249], v[0:3]
	ds_read_b128 v[190:193], v206 offset:41536
	v_mfma_f32_16x16x32_bf16 v[16:19], v[194:197], v[246:249], v[16:19]
	ds_read_b128 v[194:197], v206 offset:43840
	ds_read_b128 v[242:245], v181 offset:4672
	s_waitcnt lgkmcnt(4)
	v_mfma_f32_16x16x32_bf16 v[156:159], v[182:185], v[198:201], v[156:159]
	s_waitcnt vmcnt(7)
	ds_write_b128 v251, v[120:123] offset:36864
	s_waitcnt lgkmcnt(4)
	v_mfma_f32_16x16x32_bf16 v[152:155], v[186:189], v[198:201], v[152:155]
	s_waitcnt lgkmcnt(3)
	v_mfma_f32_16x16x32_bf16 v[148:151], v[190:193], v[198:201], v[148:151]
	v_lshl_add_u64 v[120:121], v[162:163], 1, s[44:45]
	s_nop 0
	global_load_dwordx4 v[120:123], v[120:121], off offset:256
	s_waitcnt lgkmcnt(2)
	v_mfma_f32_16x16x32_bf16 v[144:147], v[194:197], v[198:201], v[144:147]
	ds_read_b128 v[246:249], v181 offset:6976
	v_mfma_f32_16x16x32_bf16 v[108:111], v[182:185], v[202:205], v[108:111]
	v_mfma_f32_16x16x32_bf16 v[104:107], v[186:189], v[202:205], v[104:107]
	v_mfma_f32_16x16x32_bf16 v[100:103], v[190:193], v[202:205], v[100:103]
	s_waitcnt vmcnt(7)
	ds_write_b128 v252, v[124:127] offset:36864
	v_mfma_f32_16x16x32_bf16 v[96:99], v[194:197], v[202:205], v[96:99]
	ds_read_b128 v[198:201], v181 offset:9280
	s_waitcnt lgkmcnt(4)
	v_mfma_f32_16x16x32_bf16 v[92:95], v[182:185], v[242:245], v[92:95]
	v_lshl_add_u64 v[124:125], v[164:165], 1, s[44:45]
	s_nop 0
	global_load_dwordx4 v[124:127], v[124:125], off offset:256
	v_mfma_f32_16x16x32_bf16 v[88:91], v[186:189], v[242:245], v[88:91]
	v_mfma_f32_16x16x32_bf16 v[84:87], v[190:193], v[242:245], v[84:87]
	v_mfma_f32_16x16x32_bf16 v[80:83], v[194:197], v[242:245], v[80:83]
	ds_read_b128 v[202:205], v181 offset:11584
	s_waitcnt lgkmcnt(3)
	v_mfma_f32_16x16x32_bf16 v[76:79], v[182:185], v[246:249], v[76:79]
	s_waitcnt vmcnt(7)
	ds_write_b128 v253, v[136:139] offset:36864
	v_mfma_f32_16x16x32_bf16 v[72:75], v[186:189], v[246:249], v[72:75]
	v_mfma_f32_16x16x32_bf16 v[68:71], v[190:193], v[246:249], v[68:71]
	v_lshl_add_u64 v[136:137], v[166:167], 1, s[44:45]
	s_nop 0
	global_load_dwordx4 v[136:139], v[136:137], off offset:256
	v_mfma_f32_16x16x32_bf16 v[64:67], v[194:197], v[246:249], v[64:67]
	ds_read_b128 v[242:245], v181 offset:13888
	s_waitcnt lgkmcnt(3)
	v_mfma_f32_16x16x32_bf16 v[60:63], v[182:185], v[198:201], v[60:63]
	v_mfma_f32_16x16x32_bf16 v[56:59], v[186:189], v[198:201], v[56:59]
	v_mfma_f32_16x16x32_bf16 v[52:55], v[190:193], v[198:201], v[52:55]
	v_mfma_f32_16x16x32_bf16 v[48:51], v[194:197], v[198:201], v[48:51]
	ds_read_b128 v[246:249], v181 offset:16192
	s_waitcnt lgkmcnt(3)
	v_mfma_f32_16x16x32_bf16 v[44:47], v[182:185], v[202:205], v[44:47]
	v_mfma_f32_16x16x32_bf16 v[40:43], v[186:189], v[202:205], v[40:43]
	v_mfma_f32_16x16x32_bf16 v[36:39], v[190:193], v[202:205], v[36:39]
	v_mfma_f32_16x16x32_bf16 v[32:35], v[194:197], v[202:205], v[32:35]
	s_waitcnt lgkmcnt(0)
	s_barrier
	s_add_i32 s43, s43, 1
	s_cmp_lg_u32 s43, 16
	s_cbranch_scc0 .Lgm14_exit
	s_and_b32 s98, s43, 1
	s_mul_i32 s98, s98, 0x12000
	v_add3_u32 v206, s98, v171, v180
	v_add3_u32 v181, s98, v170, v180
	ds_read_b128 v[198:201], v181
	ds_read_b128 v[202:205], v181 offset:2304
	v_mfma_f32_16x16x32_bf16 v[28:31], v[182:185], v[242:245], v[28:31]
	v_mfma_f32_16x16x32_bf16 v[8:11], v[182:185], v[246:249], v[8:11]
	ds_read_b128 v[182:185], v206 offset:36864
	v_mfma_f32_16x16x32_bf16 v[24:27], v[186:189], v[242:245], v[24:27]
	v_mfma_f32_16x16x32_bf16 v[4:7], v[186:189], v[246:249], v[4:7]
	ds_read_b128 v[186:189], v206 offset:39168
	v_mfma_f32_16x16x32_bf16 v[20:23], v[190:193], v[242:245], v[20:23]
	v_mfma_f32_16x16x32_bf16 v[0:3], v[190:193], v[246:249], v[0:3]
	ds_read_b128 v[190:193], v206 offset:41472
	v_mfma_f32_16x16x32_bf16 v[12:15], v[194:197], v[242:245], v[12:15]
	v_mfma_f32_16x16x32_bf16 v[16:19], v[194:197], v[246:249], v[16:19]
	ds_read_b128 v[194:197], v206 offset:43776
	s_branch .Lgm14_main
